# MLA q up-projection GEMM: per-tile 32-byte row sum-of-squares records prefetched to LDS by two LDS-DMA loads
# speedup vs baseline: 1.0034x; 1.0034x over previous
; #define PG8_BAR __builtin_amdgcn_s_barrier()
; template <class Epi>
; __device__ __forceinline__ void gemm_phase(LAS unsigned char* lds, const Gemm g, const Epi& E) {
;     ...
;         for (int a = 0; a < 2; ++a)
; #pragma unroll
;             for (int b = 0; b < 2; ++b)
; #pragma unroll
;                 for (int m = 0; m < 4; ++m)
; #pragma unroll
;                     for (int n = 0; n < 2; ++n) acc[a][b][m][n] = (f32x4){0.f, 0.f, 0.f, 0.f};
;         cur = nxt; cA = nA; cB = nB; ++ui;
;         if (wr == 1) PG8_BAR;
.LBB0_326:
	s_andn2_b64 vcc, exec, s[76:77]
	s_cbranch_vccnz .LBB0_329
	s_and_b64 vcc, exec, s[80:81]
	s_cbranch_vccnz .Luq_ssq_skip
	v_lshl_add_u32 v156, s5, 9, v208
	v_mov_b32_e32 v157, 0
	v_subrev_u32_e32 v156, 0x100, v156
	v_readfirstlane_b32 s6, v208
	v_lshl_add_u64 v[156:157], v[156:157], 4, s[78:79]
	s_nop 1
	s_lshl_b32 s6, s6, 4
	s_add_i32 s6, s6, 0x20400
	s_mov_b32 m0, s6
	v_add_co_u32_e32 v158, vcc, 0x1000, v156
	global_load_lds_dwordx4 v[156:157], off
	v_addc_co_u32_e32 v159, vcc, 0, v157, vcc
	s_add_i32 m0, s6, 0x1000
	s_nop 0
	global_load_lds_dwordx4 v[158:159], off
.Luq_ssq_skip:
	s_add_u32 s0, s0, 0x80
	s_addc_u32 s1, s1, 0
	s_add_u32 s6, s10, 0x100
	s_addc_u32 s7, s11, 0
	s_mov_b32 s8, 0
	v_mov_b64_e32 v[2:3], 0
	v_mov_b64_e32 v[4:5], 0
	v_mov_b64_e32 v[6:7], 0
	v_mov_b64_e32 v[8:9], 0
	v_mov_b64_e32 v[10:11], 0
	v_mov_b64_e32 v[12:13], 0
	v_mov_b64_e32 v[14:15], 0
	v_mov_b64_e32 v[16:17], 0
	v_mov_b64_e32 v[18:19], 0
	v_mov_b64_e32 v[20:21], 0
	v_mov_b64_e32 v[22:23], 0
	v_mov_b64_e32 v[24:25], 0
	v_mov_b64_e32 v[26:27], 0
	v_mov_b64_e32 v[28:29], 0
	v_mov_b64_e32 v[30:31], 0
	v_mov_b64_e32 v[32:33], 0
	v_mov_b64_e32 v[34:35], 0
	v_mov_b64_e32 v[36:37], 0
	v_mov_b64_e32 v[38:39], 0
	v_mov_b64_e32 v[40:41], 0
	v_mov_b64_e32 v[42:43], 0
	v_mov_b64_e32 v[44:45], 0
	v_mov_b64_e32 v[46:47], 0
	v_mov_b64_e32 v[48:49], 0
	v_mov_b64_e32 v[50:51], 0
	v_mov_b64_e32 v[52:53], 0
	v_mov_b64_e32 v[54:55], 0
	v_mov_b64_e32 v[56:57], 0
	v_mov_b64_e32 v[58:59], 0
	v_mov_b64_e32 v[60:61], 0
	v_mov_b64_e32 v[62:63], 0
	v_mov_b64_e32 v[64:65], 0
	v_mov_b64_e32 v[66:67], 0
	v_mov_b64_e32 v[68:69], 0
	v_mov_b64_e32 v[70:71], 0
	v_mov_b64_e32 v[72:73], 0
	v_mov_b64_e32 v[74:75], 0
	v_mov_b64_e32 v[76:77], 0
	v_mov_b64_e32 v[78:79], 0
	v_mov_b64_e32 v[80:81], 0
	v_mov_b64_e32 v[82:83], 0
	v_mov_b64_e32 v[84:85], 0
	v_mov_b64_e32 v[86:87], 0
	v_mov_b64_e32 v[88:89], 0
	v_mov_b64_e32 v[90:91], 0
	v_mov_b64_e32 v[92:93], 0
	v_mov_b64_e32 v[94:95], 0
	v_mov_b64_e32 v[96:97], 0
	v_mov_b64_e32 v[98:99], 0
	v_mov_b64_e32 v[100:101], 0
	v_mov_b64_e32 v[102:103], 0
	v_mov_b64_e32 v[104:105], 0
	v_mov_b64_e32 v[106:107], 0
	v_mov_b64_e32 v[108:109], 0
	v_mov_b64_e32 v[110:111], 0
	v_mov_b64_e32 v[112:113], 0
	v_mov_b64_e32 v[114:115], 0
	v_mov_b64_e32 v[116:117], 0
	v_mov_b64_e32 v[118:119], 0
	v_mov_b64_e32 v[120:121], 0
	v_mov_b64_e32 v[122:123], 0
	v_mov_b64_e32 v[124:125], 0
	v_mov_b64_e32 v[126:127], 0
	v_mov_b64_e32 v[128:129], 0

; __device__ __forceinline__ unsigned cvtpk(float lo, float hi) { f32x2 v = {lo, hi}; bf16x2_t b = __builtin_convertvector(v, bf16x2_t); return __builtin_bit_cast(unsigned, b); }
; __device__ __forceinline__ void rope8(f32x4& v0, f32x4& v1, const float* cosr, const float* sinr, int fq) {
;     const int j0 = 8 * (fq & 1);
;     const f32x4 c0 = *(const f32x4*)(cosr + j0), c1 = *(const f32x4*)(cosr + j0 + 4), s0 = *(const f32x4*)(sinr + j0), s1 = *(const f32x4*)(sinr + j0 + 4);
;     const float sg = (fq < 2) ? -1.f : 1.f;
; #pragma unroll
;     for (int i = 0; i < 4; ++i) {
;         const float p0 = __shfl_xor(v0[i], 32), p1 = __shfl_xor(v1[i], 32);
;         v0[i] = v0[i] * c0[i] + sg * p0 * s0[i]; v1[i] = v1[i] * c1[i] + sg * p1 * s1[i];
;     }
; }
;     __device__ __forceinline__ void operator()(AccRef acc, const Unit& u, int wr, int wc, int fr, int fq) const {
;     ...
;                 const int row = row0 + ai * 128 + m * 16;
;                 const float rs = rsqrtf(ssq_sum<NS>(ssq + (size_t)row * NS) * inv_n + EPS);
;                 bf16_t* rowp = O + (size_t)row * ldc + col0;
; #pragma unroll
;                 for (int bj = 0; bj < 2; ++bj) {
;                     f32x4 v0 = acc[ai][bj][m][0] * rs, v1 = acc[ai][bj][m][1] * rs;
;                     if (ROPE) { const int g32 = u.pn * 8 + bj * 4 + wc; if (g32 % 3 == 2) { const int pos = row & (SEQ - 1); rope8(v0, v1, cost + pos * 16, sint + pos * 16, fq); } }
;                     u32x4 w; w.x = cvtpk(v0[0], v0[1]); w.y = cvtpk(v0[2], v0[3]); w.z = cvtpk(v1[0], v1[1]); w.w = cvtpk(v1[2], v1[3]);
.LBB0_331:
	v_lshl_add_u32 v156, s5, 8, v170
	v_ashrrev_i32_e32 v157, 31, v156
	v_lshlrev_b64 v[130:131], 5, v[156:157]
	v_and_b32_e32 v134, 0x1fff, v130
	v_add_u32_e32 v134, 0x21400, v134
	ds_read_b128 v[130:133], v134
	s_nop 0
	ds_read_b128 v[134:137], v134 offset:16
	s_lshl_b32 s0, s4, 3
	s_or_b32 s5, s0, s59
	s_mul_hi_i32 s0, s5, 0x55555556
	s_lshr_b32 s1, s0, 31
	s_add_i32 s0, s0, s1
	s_mul_i32 s0, s0, 3
	s_sub_i32 s6, s5, s0
	s_cmp_eq_u32 s6, 2
	s_cselect_b64 s[0:1], -1, 0
	s_cmp_lg_u32 s6, 2
	s_waitcnt lgkmcnt(0)
	v_mov_b32_e32 v158, v130
	v_mov_b32_e32 v159, v134
	v_mov_b32_e32 v134, v131
	v_pk_add_f32 v[130:131], v[158:159], v[134:135]
	v_mov_b32_e32 v134, v132
	v_mov_b32_e32 v135, v136
	v_mov_b32_e32 v136, v133
	v_pk_add_f32 v[132:133], v[134:135], v[136:137]
	s_nop 0
	v_pk_add_f32 v[130:131], v[130:131], v[132:133]
	s_nop 0
	v_add_f32_e32 v0, 0, v130
	v_add_f32_e32 v0, v0, v131
	v_fmamk_f32 v0, v0, 0x3b800000, v212
	v_cmp_gt_f32_e32 vcc, s69, v0
	v_mul_f32_e32 v130, 0x4b800000, v0
	s_nop 0
	v_cndmask_b32_e32 v0, v0, v130, vcc
	v_rsq_f32_e32 v0, v0
	s_nop 0
	v_mul_f32_e32 v130, 0x45800000, v0
	v_cndmask_b32_e32 v158, v0, v130, vcc
	v_lshlrev_b32_e32 v0, 4, v156
	v_and_b32_e32 v0, 0x7cf0, v0
	v_pk_mul_f32 v[162:163], v[124:125], v[158:159] op_sel_hi:[1,0]
	v_pk_mul_f32 v[166:167], v[122:123], v[158:159] op_sel_hi:[1,0]
	v_pk_mul_f32 v[164:165], v[128:129], v[158:159] op_sel_hi:[1,0]
	v_pk_mul_f32 v[160:161], v[126:127], v[158:159] op_sel_hi:[1,0]
	v_lshlrev_b32_e32 v0, 2, v0
	s_cbranch_scc1 .LBB0_333
	v_lshl_add_u64 v[122:123], v[148:149], 0, v[0:1]
	global_load_dwordx4 v[130:133], v[122:123], off
	global_load_dwordx4 v[126:129], v[122:123], off offset:16
	v_lshl_add_u64 v[122:123], v[150:151], 0, v[0:1]
	global_load_dwordx4 v[134:137], v[122:123], off
	s_nop 0
	global_load_dwordx4 v[122:125], v[122:123], off offset:16
	v_and_b32_e32 v159, 64, v213
	v_xor_b32_e32 v157, 32, v213
	v_add_u32_e32 v159, 64, v159
	v_cmp_lt_i32_e32 vcc, v157, v159
	v_mov_b32_e32 v176, v160
	s_waitcnt vmcnt(0)
	v_pk_mul_f32 v[130:131], v[166:167], v[130:131]
	v_cndmask_b32_e32 v157, v213, v157, vcc
	v_lshlrev_b32_e32 v157, 2, v157
	ds_bpermute_b32 v159, v157, v160
	v_mov_b32_e32 v177, v122
	v_mov_b32_e32 v168, v126
	ds_bpermute_b32 v174, v157, v166
	ds_bpermute_b32 v175, v157, v167
	s_waitcnt lgkmcnt(0)
	v_mul_f32_e32 v169, v146, v159
	v_mul_f32_e32 v122, v122, v169
	v_pk_fma_f32 v[168:169], v[176:177], v[168:169], v[122:123] op_sel_hi:[1,1,0]
	ds_bpermute_b32 v122, v157, v161
	v_pk_mul_f32 v[166:167], v[146:147], v[174:175]
	v_mov_b32_e32 v174, v127
	v_mul_f32_e32 v126, v161, v127
	v_mov_b32_e32 v176, v164
	s_waitcnt lgkmcnt(0)
	v_mul_f32_e32 v175, v146, v122
	v_mov_b32_e32 v122, v161
	v_pk_fma_f32 v[160:161], v[122:123], v[174:175], v[126:127] op_sel_hi:[1,1,0]
	ds_bpermute_b32 v123, v157, v162
	ds_bpermute_b32 v127, v157, v164
	v_mov_b32_e32 v177, v124
	v_mov_b32_e32 v174, v128
	v_mul_f32_e32 v122, v162, v132
	s_waitcnt lgkmcnt(1)
	v_mul_f32_e32 v123, v146, v123
	v_mul_f32_e32 v126, v136, v123
	ds_bpermute_b32 v123, v157, v163
	s_waitcnt lgkmcnt(1)
	v_mul_f32_e32 v175, v146, v127
	v_mul_f32_e32 v124, v124, v175
	v_pk_fma_f32 v[174:175], v[176:177], v[174:175], v[124:125] op_sel_hi:[1,1,0]
	ds_bpermute_b32 v124, v157, v165
	s_waitcnt lgkmcnt(1)
	v_mul_f32_e32 v177, v146, v123
	v_mov_b32_e32 v136, v163
	v_mov_b32_e32 v176, v133
	v_pk_mul_f32 v[132:133], v[136:137], v[176:177]
	v_pk_fma_f32 v[166:167], v[134:135], v[166:167], v[130:131]
	v_mov_b32_e32 v123, v132
	v_mov_b32_e32 v127, v133
	v_pk_add_f32 v[162:163], v[122:123], v[126:127]
	s_waitcnt lgkmcnt(0)
	v_mul_f32_e32 v123, v146, v124
	v_mov_b32_e32 v124, v165
	v_mov_b32_e32 v122, v129
	v_mul_f32_e32 v126, v125, v123
	v_pk_fma_f32 v[122:123], v[124:125], v[122:123], v[126:127] op_sel_hi:[1,1,0]
	v_mov_b32_e32 v160, v168
	v_mov_b32_e32 v164, v174
	v_mov_b32_e32 v165, v122

; __device__ __forceinline__ unsigned cvtpk(float lo, float hi) { f32x2 v = {lo, hi}; bf16x2_t b = __builtin_convertvector(v, bf16x2_t); return __builtin_bit_cast(unsigned, b); }
; __device__ __forceinline__ void rope8(f32x4& v0, f32x4& v1, const float* cosr, const float* sinr, int fq) {
;     const int j0 = 8 * (fq & 1);
;     const f32x4 c0 = *(const f32x4*)(cosr + j0), c1 = *(const f32x4*)(cosr + j0 + 4), s0 = *(const f32x4*)(sinr + j0), s1 = *(const f32x4*)(sinr + j0 + 4);
;     const float sg = (fq < 2) ? -1.f : 1.f;
; #pragma unroll
;     for (int i = 0; i < 4; ++i) {
;         const float p0 = __shfl_xor(v0[i], 32), p1 = __shfl_xor(v1[i], 32);
;         v0[i] = v0[i] * c0[i] + sg * p0 * s0[i]; v1[i] = v1[i] * c1[i] + sg * p1 * s1[i];
;     }
; }
;     __device__ __forceinline__ void operator()(AccRef acc, const Unit& u, int wr, int wc, int fr, int fq) const {
;     ...
;                 const int row = row0 + ai * 128 + m * 16;
;                 const float rs = rsqrtf(ssq_sum<NS>(ssq + (size_t)row * NS) * inv_n + EPS);
;                 bf16_t* rowp = O + (size_t)row * ldc + col0;
; #pragma unroll
;                 for (int bj = 0; bj < 2; ++bj) {
;                     f32x4 v0 = acc[ai][bj][m][0] * rs, v1 = acc[ai][bj][m][1] * rs;
;                     if (ROPE) { const int g32 = u.pn * 8 + bj * 4 + wc; if (g32 % 3 == 2) { const int pos = row & (SEQ - 1); rope8(v0, v1, cost + pos * 16, sint + pos * 16, fq); } }
;                     u32x4 w; w.x = cvtpk(v0[0], v0[1]); w.y = cvtpk(v0[2], v0[3]); w.z = cvtpk(v1[0], v1[1]); w.w = cvtpk(v1[2], v1[3]);
.LBB0_335:
	v_or_b32_e32 v124, 16, v156
	v_cvt_pk_bf16_f32 v114, v162, v163
	v_cvt_pk_bf16_f32 v115, v134, v135
	v_cvt_pk_bf16_f32 v116, v136, v137
	v_cvt_pk_bf16_f32 v117, v160, v161
	v_ashrrev_i32_e32 v125, 31, v124
	global_store_dwordx4 v[132:133], v[114:117], off offset:256
	s_nop 1
	v_lshlrev_b64 v[114:115], 5, v[124:125]
	v_and_b32_e32 v118, 0x1fff, v114
	v_add_u32_e32 v118, 0x21400, v118
	ds_read_b128 v[114:117], v118
	s_nop 0
	ds_read_b128 v[118:121], v118 offset:16
	s_waitcnt lgkmcnt(0)
	v_mov_b32_e32 v122, v114
	v_mov_b32_e32 v123, v118
	v_mov_b32_e32 v118, v115
	v_pk_add_f32 v[114:115], v[122:123], v[118:119]
	v_mov_b32_e32 v118, v116
	v_mov_b32_e32 v119, v120
	v_mov_b32_e32 v120, v117
	v_pk_add_f32 v[116:117], v[118:119], v[120:121]
	s_nop 0
	v_pk_add_f32 v[114:115], v[114:115], v[116:117]
	s_nop 0
	v_add_f32_e32 v0, 0, v114
	v_add_f32_e32 v0, v0, v115
	v_fmamk_f32 v0, v0, 0x3b800000, v212
	v_cmp_gt_f32_e32 vcc, s69, v0
	v_mul_f32_e32 v114, 0x4b800000, v0
	s_nop 0
	v_cndmask_b32_e32 v0, v0, v114, vcc
	v_rsq_f32_e32 v0, v0
	s_nop 0
	v_mul_f32_e32 v114, 0x45800000, v0
	v_cndmask_b32_e32 v122, v0, v114, vcc
	v_lshlrev_b32_e32 v0, 4, v124
	v_and_b32_e32 v0, 0x7df0, v0
	v_pk_mul_f32 v[126:127], v[106:107], v[122:123] op_sel_hi:[1,0]
	v_cndmask_b32_e64 v106, 0, 1, s[0:1]
	v_pk_mul_f32 v[128:129], v[112:113], v[122:123] op_sel_hi:[1,0]
	v_pk_mul_f32 v[134:135], v[110:111], v[122:123] op_sel_hi:[1,0]
	v_pk_mul_f32 v[132:133], v[108:109], v[122:123] op_sel_hi:[1,0]
	v_cmp_ne_u32_e64 s[40:41], 1, v106
	s_andn2_b64 vcc, exec, s[0:1]
	v_lshlrev_b32_e32 v0, 2, v0
	s_cbranch_vccnz .LBB0_337
	v_lshl_add_u64 v[106:107], v[148:149], 0, v[0:1]
	global_load_dwordx4 v[114:117], v[106:107], off
	global_load_dwordx4 v[110:113], v[106:107], off offset:16
	v_lshl_add_u64 v[106:107], v[150:151], 0, v[0:1]
	global_load_dwordx4 v[118:121], v[106:107], off
	s_nop 0
	global_load_dwordx4 v[106:109], v[106:107], off offset:16
	v_and_b32_e32 v125, 64, v213
	v_xor_b32_e32 v123, 32, v213
	v_add_u32_e32 v125, 64, v125
	v_cmp_lt_i32_e32 vcc, v123, v125
	v_mov_b32_e32 v160, v126
	s_waitcnt vmcnt(0)
	v_pk_mul_f32 v[114:115], v[134:135], v[114:115]
	v_cndmask_b32_e32 v123, v213, v123, vcc
	v_lshlrev_b32_e32 v123, 2, v123
	ds_bpermute_b32 v125, v123, v126
	v_mov_b32_e32 v161, v106
	v_mov_b32_e32 v136, v110
	ds_bpermute_b32 v158, v123, v134
	ds_bpermute_b32 v159, v123, v135
	s_waitcnt lgkmcnt(0)
	v_mul_f32_e32 v137, v146, v125
	v_mul_f32_e32 v106, v106, v137
	v_pk_fma_f32 v[136:137], v[160:161], v[136:137], v[106:107] op_sel_hi:[1,1,0]
	ds_bpermute_b32 v106, v123, v127
	v_pk_mul_f32 v[134:135], v[146:147], v[158:159]
	v_mov_b32_e32 v158, v111
	v_mul_f32_e32 v110, v127, v111
	v_mov_b32_e32 v160, v132
	s_waitcnt lgkmcnt(0)
	v_mul_f32_e32 v159, v146, v106
	v_mov_b32_e32 v106, v127
	v_pk_fma_f32 v[126:127], v[106:107], v[158:159], v[110:111] op_sel_hi:[1,1,0]
	ds_bpermute_b32 v107, v123, v128
	ds_bpermute_b32 v111, v123, v132
	v_mov_b32_e32 v161, v108
	v_mov_b32_e32 v158, v112
	v_mul_f32_e32 v106, v128, v116
	s_waitcnt lgkmcnt(1)
	v_mul_f32_e32 v107, v146, v107
	v_mul_f32_e32 v110, v120, v107
	ds_bpermute_b32 v107, v123, v129
	s_waitcnt lgkmcnt(1)
	v_mul_f32_e32 v159, v146, v111
	v_mul_f32_e32 v108, v108, v159
	v_pk_fma_f32 v[158:159], v[160:161], v[158:159], v[108:109] op_sel_hi:[1,1,0]
	ds_bpermute_b32 v108, v123, v133
	s_waitcnt lgkmcnt(1)
	v_mul_f32_e32 v161, v146, v107
	v_mov_b32_e32 v120, v129
	v_mov_b32_e32 v160, v117
	v_pk_mul_f32 v[116:117], v[120:121], v[160:161]
	v_pk_fma_f32 v[134:135], v[118:119], v[134:135], v[114:115]
	v_mov_b32_e32 v107, v116
	v_mov_b32_e32 v111, v117
	v_pk_add_f32 v[128:129], v[106:107], v[110:111]
	s_waitcnt lgkmcnt(0)
	v_mul_f32_e32 v107, v146, v108
	v_mov_b32_e32 v108, v133
	v_mov_b32_e32 v106, v113
	v_mul_f32_e32 v110, v109, v107
	v_pk_fma_f32 v[106:107], v[108:109], v[106:107], v[110:111] op_sel_hi:[1,1,0]
	v_mov_b32_e32 v126, v136
	v_mov_b32_e32 v132, v158
	v_mov_b32_e32 v133, v106

; __device__ __forceinline__ unsigned cvtpk(float lo, float hi) { f32x2 v = {lo, hi}; bf16x2_t b = __builtin_convertvector(v, bf16x2_t); return __builtin_bit_cast(unsigned, b); }
; __device__ __forceinline__ void rope8(f32x4& v0, f32x4& v1, const float* cosr, const float* sinr, int fq) {
;     const int j0 = 8 * (fq & 1);
;     const f32x4 c0 = *(const f32x4*)(cosr + j0), c1 = *(const f32x4*)(cosr + j0 + 4), s0 = *(const f32x4*)(sinr + j0), s1 = *(const f32x4*)(sinr + j0 + 4);
;     const float sg = (fq < 2) ? -1.f : 1.f;
; #pragma unroll
;     for (int i = 0; i < 4; ++i) {
;         const float p0 = __shfl_xor(v0[i], 32), p1 = __shfl_xor(v1[i], 32);
;         v0[i] = v0[i] * c0[i] + sg * p0 * s0[i]; v1[i] = v1[i] * c1[i] + sg * p1 * s1[i];
;     }
; }
;     __device__ __forceinline__ void operator()(AccRef acc, const Unit& u, int wr, int wc, int fr, int fq) const {
;     ...
;                 const int row = row0 + ai * 128 + m * 16;
;                 const float rs = rsqrtf(ssq_sum<NS>(ssq + (size_t)row * NS) * inv_n + EPS);
;                 bf16_t* rowp = O + (size_t)row * ldc + col0;
; #pragma unroll
;                 for (int bj = 0; bj < 2; ++bj) {
;                     f32x4 v0 = acc[ai][bj][m][0] * rs, v1 = acc[ai][bj][m][1] * rs;
;                     if (ROPE) { const int g32 = u.pn * 8 + bj * 4 + wc; if (g32 % 3 == 2) { const int pos = row & (SEQ - 1); rope8(v0, v1, cost + pos * 16, sint + pos * 16, fq); } }
;                     u32x4 w; w.x = cvtpk(v0[0], v0[1]); w.y = cvtpk(v0[2], v0[3]); w.z = cvtpk(v1[0], v1[1]); w.w = cvtpk(v1[2], v1[3]);
.LBB0_339:
	v_or_b32_e32 v106, 32, v156
	v_cvt_pk_bf16_f32 v98, v124, v125
	v_cvt_pk_bf16_f32 v99, v116, v117
	v_cvt_pk_bf16_f32 v100, v118, v119
	v_cvt_pk_bf16_f32 v101, v120, v121
	v_ashrrev_i32_e32 v107, 31, v106
	global_store_dwordx4 v[114:115], v[98:101], off offset:256
	s_and_b64 vcc, exec, s[40:41]
	s_nop 0
	v_lshlrev_b64 v[98:99], 5, v[106:107]
	v_and_b32_e32 v102, 0x1fff, v98
	v_add_u32_e32 v102, 0x21400, v102
	ds_read_b128 v[98:101], v102
	s_nop 0
	ds_read_b128 v[102:105], v102 offset:16
	s_waitcnt lgkmcnt(0)
	v_mov_b32_e32 v108, v98
	v_mov_b32_e32 v109, v102
	v_mov_b32_e32 v102, v99
	v_mov_b32_e32 v98, v100
	v_mov_b32_e32 v99, v104
	v_mov_b32_e32 v104, v101
	v_pk_add_f32 v[100:101], v[108:109], v[102:103]
	v_pk_add_f32 v[98:99], v[98:99], v[104:105]
	s_nop 0
	v_pk_add_f32 v[98:99], v[100:101], v[98:99]
	s_nop 0
	v_add_f32_e32 v0, 0, v98
	v_add_f32_e32 v0, v0, v99
	v_fmamk_f32 v0, v0, 0x3b800000, v212
	v_mul_f32_e32 v98, 0x4b800000, v0
	v_cmp_gt_f32_e64 s[44:45], s69, v0
	s_nop 1
	v_cndmask_b32_e64 v0, v0, v98, s[44:45]
	v_rsq_f32_e32 v0, v0
	v_lshlrev_b32_e32 v98, 4, v106
	v_and_b32_e32 v98, 0x7ef0, v98
	v_mul_f32_e32 v99, 0x45800000, v0
	v_cndmask_b32_e64 v108, v0, v99, s[44:45]
	v_pk_mul_f32 v[112:113], v[96:97], v[108:109] op_sel_hi:[1,0]
	v_pk_mul_f32 v[118:119], v[94:95], v[108:109] op_sel_hi:[1,0]
	v_pk_mul_f32 v[114:115], v[92:93], v[108:109] op_sel_hi:[1,0]
	v_pk_mul_f32 v[110:111], v[90:91], v[108:109] op_sel_hi:[1,0]
	v_lshlrev_b32_e32 v0, 2, v98
	s_cbranch_vccnz .LBB0_341
	v_lshl_add_u64 v[90:91], v[148:149], 0, v[0:1]
	global_load_dwordx4 v[98:101], v[90:91], off
	global_load_dwordx4 v[94:97], v[90:91], off offset:16
	v_lshl_add_u64 v[90:91], v[150:151], 0, v[0:1]
	global_load_dwordx4 v[102:105], v[90:91], off
	s_nop 0
	global_load_dwordx4 v[90:93], v[90:91], off offset:16
	v_and_b32_e32 v109, 64, v213
	v_xor_b32_e32 v107, 32, v213
	v_add_u32_e32 v109, 64, v109
	v_cmp_lt_i32_e32 vcc, v107, v109
	v_mov_b32_e32 v122, v110
	s_waitcnt vmcnt(0)
	v_pk_mul_f32 v[98:99], v[118:119], v[98:99]
	v_cndmask_b32_e32 v107, v213, v107, vcc
	v_lshlrev_b32_e32 v107, 2, v107
	ds_bpermute_b32 v109, v107, v110
	v_mov_b32_e32 v123, v90
	v_mov_b32_e32 v116, v94
	ds_bpermute_b32 v120, v107, v118
	ds_bpermute_b32 v121, v107, v119
	s_waitcnt lgkmcnt(0)
	v_mul_f32_e32 v117, v146, v109
	v_mul_f32_e32 v90, v90, v117
	v_pk_fma_f32 v[116:117], v[122:123], v[116:117], v[90:91] op_sel_hi:[1,1,0]
	ds_bpermute_b32 v90, v107, v111
	v_pk_mul_f32 v[118:119], v[146:147], v[120:121]
	v_mov_b32_e32 v120, v95
	v_mul_f32_e32 v94, v111, v95
	v_mov_b32_e32 v122, v114
	s_waitcnt lgkmcnt(0)
	v_mul_f32_e32 v121, v146, v90
	v_mov_b32_e32 v90, v111
	v_pk_fma_f32 v[110:111], v[90:91], v[120:121], v[94:95] op_sel_hi:[1,1,0]
	ds_bpermute_b32 v91, v107, v112
	ds_bpermute_b32 v95, v107, v114
	v_mov_b32_e32 v123, v92
	v_mov_b32_e32 v120, v96
	v_mul_f32_e32 v90, v112, v100
	s_waitcnt lgkmcnt(1)
	v_mul_f32_e32 v91, v146, v91
	v_mul_f32_e32 v94, v104, v91
	ds_bpermute_b32 v91, v107, v113
	s_waitcnt lgkmcnt(1)
	v_mul_f32_e32 v121, v146, v95
	v_mul_f32_e32 v92, v92, v121
	v_pk_fma_f32 v[120:121], v[122:123], v[120:121], v[92:93] op_sel_hi:[1,1,0]
	ds_bpermute_b32 v92, v107, v115
	s_waitcnt lgkmcnt(1)
	v_mul_f32_e32 v123, v146, v91
	v_mov_b32_e32 v104, v113
	v_mov_b32_e32 v122, v101
	v_pk_mul_f32 v[100:101], v[104:105], v[122:123]
	v_pk_fma_f32 v[118:119], v[102:103], v[118:119], v[98:99]
	v_mov_b32_e32 v91, v100
	v_mov_b32_e32 v95, v101
	v_pk_add_f32 v[112:113], v[90:91], v[94:95]
	s_waitcnt lgkmcnt(0)
	v_mul_f32_e32 v91, v146, v92
	v_mov_b32_e32 v92, v115
	v_mov_b32_e32 v90, v97
	v_mul_f32_e32 v94, v93, v91
	v_pk_fma_f32 v[90:91], v[92:93], v[90:91], v[94:95] op_sel_hi:[1,1,0]
	v_mov_b32_e32 v110, v116
	v_mov_b32_e32 v114, v120
	v_mov_b32_e32 v115, v90

; __device__ __forceinline__ unsigned cvtpk(float lo, float hi) { f32x2 v = {lo, hi}; bf16x2_t b = __builtin_convertvector(v, bf16x2_t); return __builtin_bit_cast(unsigned, b); }
; __device__ __forceinline__ void rope8(f32x4& v0, f32x4& v1, const float* cosr, const float* sinr, int fq) {
;     const int j0 = 8 * (fq & 1);
;     const f32x4 c0 = *(const f32x4*)(cosr + j0), c1 = *(const f32x4*)(cosr + j0 + 4), s0 = *(const f32x4*)(sinr + j0), s1 = *(const f32x4*)(sinr + j0 + 4);
;     const float sg = (fq < 2) ? -1.f : 1.f;
; #pragma unroll
;     for (int i = 0; i < 4; ++i) {
;         const float p0 = __shfl_xor(v0[i], 32), p1 = __shfl_xor(v1[i], 32);
;         v0[i] = v0[i] * c0[i] + sg * p0 * s0[i]; v1[i] = v1[i] * c1[i] + sg * p1 * s1[i];
;     }
; }
;     __device__ __forceinline__ void operator()(AccRef acc, const Unit& u, int wr, int wc, int fr, int fq) const {
;     ...
;                 const int row = row0 + ai * 128 + m * 16;
;                 const float rs = rsqrtf(ssq_sum<NS>(ssq + (size_t)row * NS) * inv_n + EPS);
;                 bf16_t* rowp = O + (size_t)row * ldc + col0;
; #pragma unroll
;                 for (int bj = 0; bj < 2; ++bj) {
;                     f32x4 v0 = acc[ai][bj][m][0] * rs, v1 = acc[ai][bj][m][1] * rs;
;                     if (ROPE) { const int g32 = u.pn * 8 + bj * 4 + wc; if (g32 % 3 == 2) { const int pos = row & (SEQ - 1); rope8(v0, v1, cost + pos * 16, sint + pos * 16, fq); } }
;                     u32x4 w; w.x = cvtpk(v0[0], v0[1]); w.y = cvtpk(v0[2], v0[3]); w.z = cvtpk(v1[0], v1[1]); w.w = cvtpk(v1[2], v1[3]);
.LBB0_343:
	v_or_b32_e32 v90, 48, v156
	v_cvt_pk_bf16_f32 v82, v110, v111
	v_cvt_pk_bf16_f32 v83, v100, v101
	v_cvt_pk_bf16_f32 v84, v102, v103
	v_cvt_pk_bf16_f32 v85, v104, v105
	v_ashrrev_i32_e32 v91, 31, v90
	global_store_dwordx4 v[98:99], v[82:85], off offset:256
	s_and_b64 vcc, exec, s[40:41]
	s_nop 0
	v_lshlrev_b64 v[82:83], 5, v[90:91]
	v_and_b32_e32 v86, 0x1fff, v82
	v_add_u32_e32 v86, 0x21400, v86
	ds_read_b128 v[82:85], v86
	s_nop 0
	ds_read_b128 v[86:89], v86 offset:16
	s_waitcnt lgkmcnt(0)
	v_mov_b32_e32 v92, v82
	v_mov_b32_e32 v93, v86
	v_mov_b32_e32 v86, v83
	v_mov_b32_e32 v82, v84
	v_mov_b32_e32 v83, v88
	v_mov_b32_e32 v88, v85
	v_pk_add_f32 v[84:85], v[92:93], v[86:87]
	v_pk_add_f32 v[82:83], v[82:83], v[88:89]
	s_nop 0
	v_pk_add_f32 v[82:83], v[84:85], v[82:83]
	s_nop 0
	v_add_f32_e32 v0, 0, v82
	v_add_f32_e32 v0, v0, v83
	v_fmamk_f32 v0, v0, 0x3b800000, v212
	v_mul_f32_e32 v82, 0x4b800000, v0
	v_cmp_gt_f32_e64 s[44:45], s69, v0
	s_nop 1
	v_cndmask_b32_e64 v0, v0, v82, s[44:45]
	v_rsq_f32_e32 v0, v0
	v_lshlrev_b32_e32 v82, 4, v90
	v_and_b32_e32 v82, 0x7ff0, v82
	v_mul_f32_e32 v83, 0x45800000, v0
	v_cndmask_b32_e64 v92, v0, v83, s[44:45]
	v_pk_mul_f32 v[96:97], v[80:81], v[92:93] op_sel_hi:[1,0]
	v_pk_mul_f32 v[102:103], v[78:79], v[92:93] op_sel_hi:[1,0]
	v_pk_mul_f32 v[98:99], v[76:77], v[92:93] op_sel_hi:[1,0]
	v_pk_mul_f32 v[94:95], v[74:75], v[92:93] op_sel_hi:[1,0]
	v_lshlrev_b32_e32 v0, 2, v82
	s_cbranch_vccnz .LBB0_345
	v_lshl_add_u64 v[74:75], v[148:149], 0, v[0:1]
	global_load_dwordx4 v[82:85], v[74:75], off
	global_load_dwordx4 v[78:81], v[74:75], off offset:16
	v_lshl_add_u64 v[74:75], v[150:151], 0, v[0:1]
	global_load_dwordx4 v[86:89], v[74:75], off
	s_nop 0
	global_load_dwordx4 v[74:77], v[74:75], off offset:16
	v_and_b32_e32 v93, 64, v213
	v_xor_b32_e32 v91, 32, v213
	v_add_u32_e32 v93, 64, v93
	v_cmp_lt_i32_e32 vcc, v91, v93
	v_mov_b32_e32 v106, v94
	s_waitcnt vmcnt(0)
	v_pk_mul_f32 v[82:83], v[102:103], v[82:83]
	v_cndmask_b32_e32 v91, v213, v91, vcc
	v_lshlrev_b32_e32 v91, 2, v91
	ds_bpermute_b32 v93, v91, v94
	v_mov_b32_e32 v107, v74
	v_mov_b32_e32 v100, v78
	ds_bpermute_b32 v104, v91, v102
	ds_bpermute_b32 v105, v91, v103
	s_waitcnt lgkmcnt(0)
	v_mul_f32_e32 v101, v146, v93
	v_mul_f32_e32 v74, v74, v101
	v_pk_fma_f32 v[100:101], v[106:107], v[100:101], v[74:75] op_sel_hi:[1,1,0]
	ds_bpermute_b32 v74, v91, v95
	v_pk_mul_f32 v[102:103], v[146:147], v[104:105]
	v_mov_b32_e32 v104, v79
	v_mul_f32_e32 v78, v95, v79
	v_mov_b32_e32 v106, v98
	s_waitcnt lgkmcnt(0)
	v_mul_f32_e32 v105, v146, v74
	v_mov_b32_e32 v74, v95
	v_pk_fma_f32 v[94:95], v[74:75], v[104:105], v[78:79] op_sel_hi:[1,1,0]
	ds_bpermute_b32 v75, v91, v96
	ds_bpermute_b32 v79, v91, v98
	v_mov_b32_e32 v107, v76
	v_mov_b32_e32 v104, v80
	v_mul_f32_e32 v74, v96, v84
	s_waitcnt lgkmcnt(1)
	v_mul_f32_e32 v75, v146, v75
	v_mul_f32_e32 v78, v88, v75
	ds_bpermute_b32 v75, v91, v97
	s_waitcnt lgkmcnt(1)
	v_mul_f32_e32 v105, v146, v79
	v_mul_f32_e32 v76, v76, v105
	v_pk_fma_f32 v[104:105], v[106:107], v[104:105], v[76:77] op_sel_hi:[1,1,0]
	ds_bpermute_b32 v76, v91, v99
	s_waitcnt lgkmcnt(1)
	v_mul_f32_e32 v107, v146, v75
	v_mov_b32_e32 v88, v97
	v_mov_b32_e32 v106, v85
	v_pk_mul_f32 v[84:85], v[88:89], v[106:107]
	v_pk_fma_f32 v[102:103], v[86:87], v[102:103], v[82:83]
	v_mov_b32_e32 v75, v84
	v_mov_b32_e32 v79, v85
	v_pk_add_f32 v[96:97], v[74:75], v[78:79]
	s_waitcnt lgkmcnt(0)
	v_mul_f32_e32 v75, v146, v76
	v_mov_b32_e32 v76, v99
	v_mov_b32_e32 v74, v81
	v_mul_f32_e32 v78, v77, v75
	v_pk_fma_f32 v[74:75], v[76:77], v[74:75], v[78:79] op_sel_hi:[1,1,0]
	v_mov_b32_e32 v94, v100
	v_mov_b32_e32 v98, v104
	v_mov_b32_e32 v99, v74

; __device__ __forceinline__ unsigned cvtpk(float lo, float hi) { f32x2 v = {lo, hi}; bf16x2_t b = __builtin_convertvector(v, bf16x2_t); return __builtin_bit_cast(unsigned, b); }
; __device__ __forceinline__ void rope8(f32x4& v0, f32x4& v1, const float* cosr, const float* sinr, int fq) {
;     const int j0 = 8 * (fq & 1);
;     const f32x4 c0 = *(const f32x4*)(cosr + j0), c1 = *(const f32x4*)(cosr + j0 + 4), s0 = *(const f32x4*)(sinr + j0), s1 = *(const f32x4*)(sinr + j0 + 4);
;     const float sg = (fq < 2) ? -1.f : 1.f;
; #pragma unroll
;     for (int i = 0; i < 4; ++i) {
;         const float p0 = __shfl_xor(v0[i], 32), p1 = __shfl_xor(v1[i], 32);
;         v0[i] = v0[i] * c0[i] + sg * p0 * s0[i]; v1[i] = v1[i] * c1[i] + sg * p1 * s1[i];
;     }
; }
;     __device__ __forceinline__ void operator()(AccRef acc, const Unit& u, int wr, int wc, int fr, int fq) const {
;     ...
;                 const int row = row0 + ai * 128 + m * 16;
;                 const float rs = rsqrtf(ssq_sum<NS>(ssq + (size_t)row * NS) * inv_n + EPS);
;                 bf16_t* rowp = O + (size_t)row * ldc + col0;
; #pragma unroll
;                 for (int bj = 0; bj < 2; ++bj) {
;                     f32x4 v0 = acc[ai][bj][m][0] * rs, v1 = acc[ai][bj][m][1] * rs;
;                     if (ROPE) { const int g32 = u.pn * 8 + bj * 4 + wc; if (g32 % 3 == 2) { const int pos = row & (SEQ - 1); rope8(v0, v1, cost + pos * 16, sint + pos * 16, fq); } }
;                     u32x4 w; w.x = cvtpk(v0[0], v0[1]); w.y = cvtpk(v0[2], v0[3]); w.z = cvtpk(v1[0], v1[1]); w.w = cvtpk(v1[2], v1[3]);
.LBB0_347:
	v_add_u32_e32 v74, 0x80, v156
	v_cvt_pk_bf16_f32 v66, v94, v95
	v_cvt_pk_bf16_f32 v67, v84, v85
	v_cvt_pk_bf16_f32 v68, v86, v87
	v_cvt_pk_bf16_f32 v69, v88, v89
	v_ashrrev_i32_e32 v75, 31, v74
	global_store_dwordx4 v[82:83], v[66:69], off offset:256
	s_and_b64 vcc, exec, s[40:41]
	s_nop 0
	v_lshlrev_b64 v[66:67], 5, v[74:75]
	v_and_b32_e32 v70, 0x1fff, v66
	v_add_u32_e32 v70, 0x21400, v70
	ds_read_b128 v[66:69], v70
	s_nop 0
	ds_read_b128 v[70:73], v70 offset:16
	s_waitcnt lgkmcnt(0)
	v_mov_b32_e32 v76, v66
	v_mov_b32_e32 v77, v70
	v_mov_b32_e32 v70, v67
	v_mov_b32_e32 v66, v68
	v_mov_b32_e32 v67, v72
	v_mov_b32_e32 v72, v69
	v_pk_add_f32 v[68:69], v[76:77], v[70:71]
	v_pk_add_f32 v[66:67], v[66:67], v[72:73]
	s_nop 0
	v_pk_add_f32 v[66:67], v[68:69], v[66:67]
	s_nop 0
	v_add_f32_e32 v0, 0, v66
	v_add_f32_e32 v0, v0, v67
	v_fmamk_f32 v0, v0, 0x3b800000, v212
	v_mul_f32_e32 v66, 0x4b800000, v0
	v_cmp_gt_f32_e64 s[44:45], s69, v0
	s_nop 1
	v_cndmask_b32_e64 v0, v0, v66, s[44:45]
	v_rsq_f32_e32 v0, v0
	v_lshlrev_b32_e32 v66, 4, v74
	v_and_b32_e32 v66, 0x7cf0, v66
	v_mul_f32_e32 v67, 0x45800000, v0
	v_cndmask_b32_e64 v76, v0, v67, s[44:45]
	v_pk_mul_f32 v[80:81], v[64:65], v[76:77] op_sel_hi:[1,0]
	v_pk_mul_f32 v[86:87], v[62:63], v[76:77] op_sel_hi:[1,0]
	v_pk_mul_f32 v[82:83], v[60:61], v[76:77] op_sel_hi:[1,0]
	v_pk_mul_f32 v[78:79], v[58:59], v[76:77] op_sel_hi:[1,0]
	v_lshlrev_b32_e32 v0, 2, v66
	s_cbranch_vccnz .LBB0_349
	v_lshl_add_u64 v[58:59], v[148:149], 0, v[0:1]
	global_load_dwordx4 v[66:69], v[58:59], off
	global_load_dwordx4 v[62:65], v[58:59], off offset:16
	v_lshl_add_u64 v[58:59], v[150:151], 0, v[0:1]
	global_load_dwordx4 v[70:73], v[58:59], off
	s_nop 0
	global_load_dwordx4 v[58:61], v[58:59], off offset:16
	v_and_b32_e32 v77, 64, v213
	v_xor_b32_e32 v75, 32, v213
	v_add_u32_e32 v77, 64, v77
	v_cmp_lt_i32_e32 vcc, v75, v77
	v_mov_b32_e32 v90, v78
	s_waitcnt vmcnt(0)
	v_pk_mul_f32 v[66:67], v[86:87], v[66:67]
	v_cndmask_b32_e32 v75, v213, v75, vcc
	v_lshlrev_b32_e32 v75, 2, v75
	ds_bpermute_b32 v77, v75, v78
	v_mov_b32_e32 v91, v58
	v_mov_b32_e32 v84, v62
	ds_bpermute_b32 v88, v75, v86
	ds_bpermute_b32 v89, v75, v87
	s_waitcnt lgkmcnt(0)
	v_mul_f32_e32 v85, v146, v77
	v_mul_f32_e32 v58, v58, v85
	v_pk_fma_f32 v[84:85], v[90:91], v[84:85], v[58:59] op_sel_hi:[1,1,0]
	ds_bpermute_b32 v58, v75, v79
	v_pk_mul_f32 v[86:87], v[146:147], v[88:89]
	v_mov_b32_e32 v88, v63
	v_mul_f32_e32 v62, v79, v63
	v_mov_b32_e32 v90, v82
	s_waitcnt lgkmcnt(0)
	v_mul_f32_e32 v89, v146, v58
	v_mov_b32_e32 v58, v79
	v_pk_fma_f32 v[78:79], v[58:59], v[88:89], v[62:63] op_sel_hi:[1,1,0]
	ds_bpermute_b32 v59, v75, v80
	ds_bpermute_b32 v63, v75, v82
	v_mov_b32_e32 v91, v60
	v_mov_b32_e32 v88, v64
	v_mul_f32_e32 v58, v80, v68
	s_waitcnt lgkmcnt(1)
	v_mul_f32_e32 v59, v146, v59
	v_mul_f32_e32 v62, v72, v59
	ds_bpermute_b32 v59, v75, v81
	s_waitcnt lgkmcnt(1)
	v_mul_f32_e32 v89, v146, v63
	v_mul_f32_e32 v60, v60, v89
	v_pk_fma_f32 v[88:89], v[90:91], v[88:89], v[60:61] op_sel_hi:[1,1,0]
	ds_bpermute_b32 v60, v75, v83
	s_waitcnt lgkmcnt(1)
	v_mul_f32_e32 v91, v146, v59
	v_mov_b32_e32 v72, v81
	v_mov_b32_e32 v90, v69
	v_pk_mul_f32 v[68:69], v[72:73], v[90:91]
	v_pk_fma_f32 v[86:87], v[70:71], v[86:87], v[66:67]
	v_mov_b32_e32 v59, v68
	v_mov_b32_e32 v63, v69
	v_pk_add_f32 v[80:81], v[58:59], v[62:63]
	s_waitcnt lgkmcnt(0)
	v_mul_f32_e32 v59, v146, v60
	v_mov_b32_e32 v60, v83
	v_mov_b32_e32 v58, v65
	v_mul_f32_e32 v62, v61, v59
	v_pk_fma_f32 v[58:59], v[60:61], v[58:59], v[62:63] op_sel_hi:[1,1,0]
	v_mov_b32_e32 v78, v84
	v_mov_b32_e32 v82, v88
	v_mov_b32_e32 v83, v58

; __device__ __forceinline__ unsigned cvtpk(float lo, float hi) { f32x2 v = {lo, hi}; bf16x2_t b = __builtin_convertvector(v, bf16x2_t); return __builtin_bit_cast(unsigned, b); }
; __device__ __forceinline__ void rope8(f32x4& v0, f32x4& v1, const float* cosr, const float* sinr, int fq) {
;     const int j0 = 8 * (fq & 1);
;     const f32x4 c0 = *(const f32x4*)(cosr + j0), c1 = *(const f32x4*)(cosr + j0 + 4), s0 = *(const f32x4*)(sinr + j0), s1 = *(const f32x4*)(sinr + j0 + 4);
;     const float sg = (fq < 2) ? -1.f : 1.f;
; #pragma unroll
;     for (int i = 0; i < 4; ++i) {
;         const float p0 = __shfl_xor(v0[i], 32), p1 = __shfl_xor(v1[i], 32);
;         v0[i] = v0[i] * c0[i] + sg * p0 * s0[i]; v1[i] = v1[i] * c1[i] + sg * p1 * s1[i];
;     }
; }
;     __device__ __forceinline__ void operator()(AccRef acc, const Unit& u, int wr, int wc, int fr, int fq) const {
;     ...
;                 const int row = row0 + ai * 128 + m * 16;
;                 const float rs = rsqrtf(ssq_sum<NS>(ssq + (size_t)row * NS) * inv_n + EPS);
;                 bf16_t* rowp = O + (size_t)row * ldc + col0;
; #pragma unroll
;                 for (int bj = 0; bj < 2; ++bj) {
;                     f32x4 v0 = acc[ai][bj][m][0] * rs, v1 = acc[ai][bj][m][1] * rs;
;                     if (ROPE) { const int g32 = u.pn * 8 + bj * 4 + wc; if (g32 % 3 == 2) { const int pos = row & (SEQ - 1); rope8(v0, v1, cost + pos * 16, sint + pos * 16, fq); } }
;                     u32x4 w; w.x = cvtpk(v0[0], v0[1]); w.y = cvtpk(v0[2], v0[3]); w.z = cvtpk(v1[0], v1[1]); w.w = cvtpk(v1[2], v1[3]);
.LBB0_351:
	v_add_u32_e32 v58, 0x90, v156
	v_cvt_pk_bf16_f32 v50, v78, v79
	v_cvt_pk_bf16_f32 v51, v68, v69
	v_cvt_pk_bf16_f32 v52, v70, v71
	v_cvt_pk_bf16_f32 v53, v72, v73
	v_ashrrev_i32_e32 v59, 31, v58
	global_store_dwordx4 v[66:67], v[50:53], off offset:256
	s_and_b64 vcc, exec, s[40:41]
	s_nop 0
	v_lshlrev_b64 v[50:51], 5, v[58:59]
	v_and_b32_e32 v54, 0x1fff, v50
	v_add_u32_e32 v54, 0x21400, v54
	ds_read_b128 v[50:53], v54
	s_nop 0
	ds_read_b128 v[54:57], v54 offset:16
	s_waitcnt lgkmcnt(0)
	v_mov_b32_e32 v60, v50
	v_mov_b32_e32 v61, v54
	v_mov_b32_e32 v54, v51
	v_mov_b32_e32 v50, v52
	v_mov_b32_e32 v51, v56
	v_mov_b32_e32 v56, v53
	v_pk_add_f32 v[52:53], v[60:61], v[54:55]
	v_pk_add_f32 v[50:51], v[50:51], v[56:57]
	s_nop 0
	v_pk_add_f32 v[50:51], v[52:53], v[50:51]
	s_nop 0
	v_add_f32_e32 v0, 0, v50
	v_add_f32_e32 v0, v0, v51
	v_fmamk_f32 v0, v0, 0x3b800000, v212
	v_mul_f32_e32 v50, 0x4b800000, v0
	v_cmp_gt_f32_e64 s[44:45], s69, v0
	s_nop 1
	v_cndmask_b32_e64 v0, v0, v50, s[44:45]
	v_rsq_f32_e32 v0, v0
	v_lshlrev_b32_e32 v50, 4, v58
	v_and_b32_e32 v50, 0x7df0, v50
	v_mul_f32_e32 v51, 0x45800000, v0
	v_cndmask_b32_e64 v60, v0, v51, s[44:45]
	v_pk_mul_f32 v[64:65], v[48:49], v[60:61] op_sel_hi:[1,0]
	v_pk_mul_f32 v[70:71], v[46:47], v[60:61] op_sel_hi:[1,0]
	v_pk_mul_f32 v[66:67], v[44:45], v[60:61] op_sel_hi:[1,0]
	v_pk_mul_f32 v[62:63], v[42:43], v[60:61] op_sel_hi:[1,0]
	v_lshlrev_b32_e32 v0, 2, v50
	s_cbranch_vccnz .LBB0_353
	v_lshl_add_u64 v[42:43], v[148:149], 0, v[0:1]
	global_load_dwordx4 v[50:53], v[42:43], off
	global_load_dwordx4 v[46:49], v[42:43], off offset:16
	v_lshl_add_u64 v[42:43], v[150:151], 0, v[0:1]
	global_load_dwordx4 v[54:57], v[42:43], off
	s_nop 0
	global_load_dwordx4 v[42:45], v[42:43], off offset:16
	v_and_b32_e32 v61, 64, v213
	v_xor_b32_e32 v59, 32, v213
	v_add_u32_e32 v61, 64, v61
	v_cmp_lt_i32_e32 vcc, v59, v61
	v_mov_b32_e32 v74, v62
	s_waitcnt vmcnt(0)
	v_pk_mul_f32 v[50:51], v[70:71], v[50:51]
	v_cndmask_b32_e32 v59, v213, v59, vcc
	v_lshlrev_b32_e32 v59, 2, v59
	ds_bpermute_b32 v61, v59, v62
	v_mov_b32_e32 v75, v42
	v_mov_b32_e32 v68, v46
	ds_bpermute_b32 v72, v59, v70
	ds_bpermute_b32 v73, v59, v71
	s_waitcnt lgkmcnt(0)
	v_mul_f32_e32 v69, v146, v61
	v_mul_f32_e32 v42, v42, v69
	v_pk_fma_f32 v[68:69], v[74:75], v[68:69], v[42:43] op_sel_hi:[1,1,0]
	ds_bpermute_b32 v42, v59, v63
	v_pk_mul_f32 v[70:71], v[146:147], v[72:73]
	v_mov_b32_e32 v72, v47
	v_mul_f32_e32 v46, v63, v47
	v_mov_b32_e32 v74, v66
	s_waitcnt lgkmcnt(0)
	v_mul_f32_e32 v73, v146, v42
	v_mov_b32_e32 v42, v63
	v_pk_fma_f32 v[62:63], v[42:43], v[72:73], v[46:47] op_sel_hi:[1,1,0]
	ds_bpermute_b32 v43, v59, v64
	ds_bpermute_b32 v47, v59, v66
	v_mov_b32_e32 v75, v44
	v_mov_b32_e32 v72, v48
	v_mul_f32_e32 v42, v64, v52
	s_waitcnt lgkmcnt(1)
	v_mul_f32_e32 v43, v146, v43
	v_mul_f32_e32 v46, v56, v43
	ds_bpermute_b32 v43, v59, v65
	s_waitcnt lgkmcnt(1)
	v_mul_f32_e32 v73, v146, v47
	v_mul_f32_e32 v44, v44, v73
	v_pk_fma_f32 v[72:73], v[74:75], v[72:73], v[44:45] op_sel_hi:[1,1,0]
	ds_bpermute_b32 v44, v59, v67
	s_waitcnt lgkmcnt(1)
	v_mul_f32_e32 v75, v146, v43
	v_mov_b32_e32 v56, v65
	v_mov_b32_e32 v74, v53
	v_pk_mul_f32 v[52:53], v[56:57], v[74:75]
	v_pk_fma_f32 v[70:71], v[54:55], v[70:71], v[50:51]
	v_mov_b32_e32 v43, v52
	v_mov_b32_e32 v47, v53
	v_pk_add_f32 v[64:65], v[42:43], v[46:47]
	s_waitcnt lgkmcnt(0)
	v_mul_f32_e32 v43, v146, v44
	v_mov_b32_e32 v44, v67
	v_mov_b32_e32 v42, v49
	v_mul_f32_e32 v46, v45, v43
	v_pk_fma_f32 v[42:43], v[44:45], v[42:43], v[46:47] op_sel_hi:[1,1,0]
	v_mov_b32_e32 v62, v68
	v_mov_b32_e32 v66, v72
	v_mov_b32_e32 v67, v42

; __device__ __forceinline__ unsigned cvtpk(float lo, float hi) { f32x2 v = {lo, hi}; bf16x2_t b = __builtin_convertvector(v, bf16x2_t); return __builtin_bit_cast(unsigned, b); }
; __device__ __forceinline__ void rope8(f32x4& v0, f32x4& v1, const float* cosr, const float* sinr, int fq) {
;     const int j0 = 8 * (fq & 1);
;     const f32x4 c0 = *(const f32x4*)(cosr + j0), c1 = *(const f32x4*)(cosr + j0 + 4), s0 = *(const f32x4*)(sinr + j0), s1 = *(const f32x4*)(sinr + j0 + 4);
;     const float sg = (fq < 2) ? -1.f : 1.f;
; #pragma unroll
;     for (int i = 0; i < 4; ++i) {
;         const float p0 = __shfl_xor(v0[i], 32), p1 = __shfl_xor(v1[i], 32);
;         v0[i] = v0[i] * c0[i] + sg * p0 * s0[i]; v1[i] = v1[i] * c1[i] + sg * p1 * s1[i];
;     }
; }
;     __device__ __forceinline__ void operator()(AccRef acc, const Unit& u, int wr, int wc, int fr, int fq) const {
;     ...
;                 const int row = row0 + ai * 128 + m * 16;
;                 const float rs = rsqrtf(ssq_sum<NS>(ssq + (size_t)row * NS) * inv_n + EPS);
;                 bf16_t* rowp = O + (size_t)row * ldc + col0;
; #pragma unroll
;                 for (int bj = 0; bj < 2; ++bj) {
;                     f32x4 v0 = acc[ai][bj][m][0] * rs, v1 = acc[ai][bj][m][1] * rs;
;                     if (ROPE) { const int g32 = u.pn * 8 + bj * 4 + wc; if (g32 % 3 == 2) { const int pos = row & (SEQ - 1); rope8(v0, v1, cost + pos * 16, sint + pos * 16, fq); } }
;                     u32x4 w; w.x = cvtpk(v0[0], v0[1]); w.y = cvtpk(v0[2], v0[3]); w.z = cvtpk(v1[0], v1[1]); w.w = cvtpk(v1[2], v1[3]);
.LBB0_355:
	v_add_u32_e32 v42, 0xa0, v156
	v_cvt_pk_bf16_f32 v34, v62, v63
	v_cvt_pk_bf16_f32 v35, v52, v53
	v_cvt_pk_bf16_f32 v36, v54, v55
	v_cvt_pk_bf16_f32 v37, v56, v57
	v_ashrrev_i32_e32 v43, 31, v42
	global_store_dwordx4 v[50:51], v[34:37], off offset:256
	s_and_b64 vcc, exec, s[40:41]
	s_nop 0
	v_lshlrev_b64 v[34:35], 5, v[42:43]
	v_and_b32_e32 v38, 0x1fff, v34
	v_add_u32_e32 v38, 0x21400, v38
	ds_read_b128 v[34:37], v38
	s_nop 0
	ds_read_b128 v[38:41], v38 offset:16
	s_waitcnt lgkmcnt(0)
	v_mov_b32_e32 v44, v34
	v_mov_b32_e32 v45, v38
	v_mov_b32_e32 v38, v35
	v_mov_b32_e32 v34, v36
	v_mov_b32_e32 v35, v40
	v_mov_b32_e32 v40, v37
	v_pk_add_f32 v[36:37], v[44:45], v[38:39]
	v_pk_add_f32 v[34:35], v[34:35], v[40:41]
	s_nop 0
	v_pk_add_f32 v[34:35], v[36:37], v[34:35]
	s_nop 0
	v_add_f32_e32 v0, 0, v34
	v_add_f32_e32 v0, v0, v35
	v_fmamk_f32 v0, v0, 0x3b800000, v212
	v_mul_f32_e32 v34, 0x4b800000, v0
	v_cmp_gt_f32_e64 s[44:45], s69, v0
	s_nop 1
	v_cndmask_b32_e64 v0, v0, v34, s[44:45]
	v_rsq_f32_e32 v0, v0
	v_lshlrev_b32_e32 v34, 4, v42
	v_and_b32_e32 v34, 0x7ef0, v34
	v_mul_f32_e32 v35, 0x45800000, v0
	v_cndmask_b32_e64 v44, v0, v35, s[44:45]
	v_pk_mul_f32 v[48:49], v[32:33], v[44:45] op_sel_hi:[1,0]
	v_pk_mul_f32 v[54:55], v[30:31], v[44:45] op_sel_hi:[1,0]
	v_pk_mul_f32 v[50:51], v[28:29], v[44:45] op_sel_hi:[1,0]
	v_pk_mul_f32 v[46:47], v[26:27], v[44:45] op_sel_hi:[1,0]
	v_lshlrev_b32_e32 v0, 2, v34
	s_cbranch_vccnz .LBB0_357
	v_lshl_add_u64 v[26:27], v[148:149], 0, v[0:1]
	global_load_dwordx4 v[34:37], v[26:27], off
	global_load_dwordx4 v[30:33], v[26:27], off offset:16
	v_lshl_add_u64 v[26:27], v[150:151], 0, v[0:1]
	global_load_dwordx4 v[38:41], v[26:27], off
	s_nop 0
	global_load_dwordx4 v[26:29], v[26:27], off offset:16
	v_and_b32_e32 v45, 64, v213
	v_xor_b32_e32 v43, 32, v213
	v_add_u32_e32 v45, 64, v45
	v_cmp_lt_i32_e32 vcc, v43, v45
	v_mov_b32_e32 v58, v46
	s_waitcnt vmcnt(0)
	v_pk_mul_f32 v[34:35], v[54:55], v[34:35]
	v_cndmask_b32_e32 v43, v213, v43, vcc
	v_lshlrev_b32_e32 v43, 2, v43
	ds_bpermute_b32 v45, v43, v46
	v_mov_b32_e32 v59, v26
	v_mov_b32_e32 v52, v30
	ds_bpermute_b32 v56, v43, v54
	ds_bpermute_b32 v57, v43, v55
	s_waitcnt lgkmcnt(0)
	v_mul_f32_e32 v53, v146, v45
	v_mul_f32_e32 v26, v26, v53
	v_pk_fma_f32 v[52:53], v[58:59], v[52:53], v[26:27] op_sel_hi:[1,1,0]
	ds_bpermute_b32 v26, v43, v47
	v_pk_mul_f32 v[54:55], v[146:147], v[56:57]
	v_mov_b32_e32 v56, v31
	v_mul_f32_e32 v30, v47, v31
	v_mov_b32_e32 v58, v50
	s_waitcnt lgkmcnt(0)
	v_mul_f32_e32 v57, v146, v26
	v_mov_b32_e32 v26, v47
	v_pk_fma_f32 v[46:47], v[26:27], v[56:57], v[30:31] op_sel_hi:[1,1,0]
	ds_bpermute_b32 v27, v43, v48
	ds_bpermute_b32 v31, v43, v50
	v_mov_b32_e32 v59, v28
	v_mov_b32_e32 v56, v32
	v_mul_f32_e32 v26, v48, v36
	s_waitcnt lgkmcnt(1)
	v_mul_f32_e32 v27, v146, v27
	v_mul_f32_e32 v30, v40, v27
	ds_bpermute_b32 v27, v43, v49
	s_waitcnt lgkmcnt(1)
	v_mul_f32_e32 v57, v146, v31
	v_mul_f32_e32 v28, v28, v57
	v_pk_fma_f32 v[56:57], v[58:59], v[56:57], v[28:29] op_sel_hi:[1,1,0]
	ds_bpermute_b32 v28, v43, v51
	s_waitcnt lgkmcnt(1)
	v_mul_f32_e32 v59, v146, v27
	v_mov_b32_e32 v40, v49
	v_mov_b32_e32 v58, v37
	v_pk_mul_f32 v[36:37], v[40:41], v[58:59]
	v_pk_fma_f32 v[54:55], v[38:39], v[54:55], v[34:35]
	v_mov_b32_e32 v27, v36
	v_mov_b32_e32 v31, v37
	v_pk_add_f32 v[48:49], v[26:27], v[30:31]
	s_waitcnt lgkmcnt(0)
	v_mul_f32_e32 v27, v146, v28
	v_mov_b32_e32 v28, v51
	v_mov_b32_e32 v26, v33
	v_mul_f32_e32 v30, v29, v27
	v_pk_fma_f32 v[26:27], v[28:29], v[26:27], v[30:31] op_sel_hi:[1,1,0]
	v_mov_b32_e32 v46, v52
	v_mov_b32_e32 v50, v56
	v_mov_b32_e32 v51, v26

; __device__ __forceinline__ unsigned cvtpk(float lo, float hi) { f32x2 v = {lo, hi}; bf16x2_t b = __builtin_convertvector(v, bf16x2_t); return __builtin_bit_cast(unsigned, b); }
; __device__ __forceinline__ void rope8(f32x4& v0, f32x4& v1, const float* cosr, const float* sinr, int fq) {
;     const int j0 = 8 * (fq & 1);
;     const f32x4 c0 = *(const f32x4*)(cosr + j0), c1 = *(const f32x4*)(cosr + j0 + 4), s0 = *(const f32x4*)(sinr + j0), s1 = *(const f32x4*)(sinr + j0 + 4);
;     const float sg = (fq < 2) ? -1.f : 1.f;
; #pragma unroll
;     for (int i = 0; i < 4; ++i) {
;         const float p0 = __shfl_xor(v0[i], 32), p1 = __shfl_xor(v1[i], 32);
;         v0[i] = v0[i] * c0[i] + sg * p0 * s0[i]; v1[i] = v1[i] * c1[i] + sg * p1 * s1[i];
;     }
; }
;     __device__ __forceinline__ void operator()(AccRef acc, const Unit& u, int wr, int wc, int fr, int fq) const {
;     ...
;                 const int row = row0 + ai * 128 + m * 16;
;                 const float rs = rsqrtf(ssq_sum<NS>(ssq + (size_t)row * NS) * inv_n + EPS);
;                 bf16_t* rowp = O + (size_t)row * ldc + col0;
; #pragma unroll
;                 for (int bj = 0; bj < 2; ++bj) {
;                     f32x4 v0 = acc[ai][bj][m][0] * rs, v1 = acc[ai][bj][m][1] * rs;
;                     if (ROPE) { const int g32 = u.pn * 8 + bj * 4 + wc; if (g32 % 3 == 2) { const int pos = row & (SEQ - 1); rope8(v0, v1, cost + pos * 16, sint + pos * 16, fq); } }
;                     u32x4 w; w.x = cvtpk(v0[0], v0[1]); w.y = cvtpk(v0[2], v0[3]); w.z = cvtpk(v1[0], v1[1]); w.w = cvtpk(v1[2], v1[3]);
.LBB0_359:
	v_add_u32_e32 v26, 0xb0, v156
	v_cvt_pk_bf16_f32 v18, v46, v47
	v_cvt_pk_bf16_f32 v19, v36, v37
	v_cvt_pk_bf16_f32 v20, v38, v39
	v_cvt_pk_bf16_f32 v21, v40, v41
	v_ashrrev_i32_e32 v27, 31, v26
	global_store_dwordx4 v[34:35], v[18:21], off offset:256
	s_and_b64 vcc, exec, s[40:41]
	s_nop 0
	v_lshlrev_b64 v[18:19], 5, v[26:27]
	v_and_b32_e32 v22, 0x1fff, v18
	v_add_u32_e32 v22, 0x21400, v22
	ds_read_b128 v[18:21], v22
	s_nop 0
	ds_read_b128 v[22:25], v22 offset:16
	s_waitcnt lgkmcnt(0)
	v_mov_b32_e32 v28, v18
	v_mov_b32_e32 v29, v22
	v_mov_b32_e32 v22, v19
	v_mov_b32_e32 v18, v20
	v_mov_b32_e32 v19, v24
	v_mov_b32_e32 v24, v21
	v_pk_add_f32 v[20:21], v[28:29], v[22:23]
	v_pk_add_f32 v[18:19], v[18:19], v[24:25]
	s_nop 0
	v_pk_add_f32 v[18:19], v[20:21], v[18:19]
	s_nop 0
	v_add_f32_e32 v0, 0, v18
	v_add_f32_e32 v0, v0, v19
	v_fmamk_f32 v0, v0, 0x3b800000, v212
	v_mul_f32_e32 v18, 0x4b800000, v0
	v_cmp_gt_f32_e64 s[44:45], s69, v0
	s_nop 1
	v_cndmask_b32_e64 v0, v0, v18, s[44:45]
	v_rsq_f32_e32 v0, v0
	v_lshlrev_b32_e32 v18, 4, v26
	v_and_b32_e32 v18, 0x7ff0, v18
	v_mul_f32_e32 v19, 0x45800000, v0
	v_cndmask_b32_e64 v28, v0, v19, s[44:45]
	v_pk_mul_f32 v[32:33], v[16:17], v[28:29] op_sel_hi:[1,0]
	v_pk_mul_f32 v[38:39], v[14:15], v[28:29] op_sel_hi:[1,0]
	v_pk_mul_f32 v[34:35], v[12:13], v[28:29] op_sel_hi:[1,0]
	v_pk_mul_f32 v[30:31], v[10:11], v[28:29] op_sel_hi:[1,0]
	v_lshlrev_b32_e32 v0, 2, v18
	s_cbranch_vccnz .LBB0_361
	v_lshl_add_u64 v[10:11], v[148:149], 0, v[0:1]
	global_load_dwordx4 v[18:21], v[10:11], off
	global_load_dwordx4 v[14:17], v[10:11], off offset:16
	v_lshl_add_u64 v[10:11], v[150:151], 0, v[0:1]
	global_load_dwordx4 v[22:25], v[10:11], off
	s_nop 0
	global_load_dwordx4 v[10:13], v[10:11], off offset:16
	v_and_b32_e32 v29, 64, v213
	v_xor_b32_e32 v27, 32, v213
	v_add_u32_e32 v29, 64, v29
	v_cmp_lt_i32_e32 vcc, v27, v29
	v_mov_b32_e32 v42, v30
	s_waitcnt vmcnt(0)
	v_pk_mul_f32 v[18:19], v[38:39], v[18:19]
	v_cndmask_b32_e32 v27, v213, v27, vcc
	v_lshlrev_b32_e32 v27, 2, v27
	ds_bpermute_b32 v29, v27, v30
	v_mov_b32_e32 v43, v10
	v_mov_b32_e32 v36, v14
	ds_bpermute_b32 v40, v27, v38
	ds_bpermute_b32 v41, v27, v39
	s_waitcnt lgkmcnt(0)
	v_mul_f32_e32 v37, v146, v29
	v_mul_f32_e32 v10, v10, v37
	v_pk_fma_f32 v[36:37], v[42:43], v[36:37], v[10:11] op_sel_hi:[1,1,0]
	ds_bpermute_b32 v10, v27, v31
	v_pk_mul_f32 v[38:39], v[146:147], v[40:41]
	v_mov_b32_e32 v40, v15
	v_mul_f32_e32 v14, v31, v15
	v_mov_b32_e32 v42, v34
	s_waitcnt lgkmcnt(0)
	v_mul_f32_e32 v41, v146, v10
	v_mov_b32_e32 v10, v31
	v_pk_fma_f32 v[30:31], v[10:11], v[40:41], v[14:15] op_sel_hi:[1,1,0]
	ds_bpermute_b32 v11, v27, v32
	ds_bpermute_b32 v15, v27, v34
	v_mov_b32_e32 v43, v12
	v_mov_b32_e32 v40, v16
	v_mul_f32_e32 v10, v32, v20
	s_waitcnt lgkmcnt(1)
	v_mul_f32_e32 v11, v146, v11
	v_mul_f32_e32 v14, v24, v11
	ds_bpermute_b32 v11, v27, v33
	s_waitcnt lgkmcnt(1)
	v_mul_f32_e32 v41, v146, v15
	v_mul_f32_e32 v12, v12, v41
	v_pk_fma_f32 v[40:41], v[42:43], v[40:41], v[12:13] op_sel_hi:[1,1,0]
	ds_bpermute_b32 v12, v27, v35
	s_waitcnt lgkmcnt(1)
	v_mul_f32_e32 v43, v146, v11
	v_mov_b32_e32 v24, v33
	v_mov_b32_e32 v42, v21
	v_pk_mul_f32 v[20:21], v[24:25], v[42:43]
	v_pk_fma_f32 v[38:39], v[22:23], v[38:39], v[18:19]
	v_mov_b32_e32 v11, v20
	v_mov_b32_e32 v15, v21
	v_pk_add_f32 v[32:33], v[10:11], v[14:15]
	s_waitcnt lgkmcnt(0)
	v_mul_f32_e32 v11, v146, v12
	v_mov_b32_e32 v12, v35
	v_mov_b32_e32 v10, v17
	v_mul_f32_e32 v14, v13, v11
	v_pk_fma_f32 v[10:11], v[12:13], v[10:11], v[14:15] op_sel_hi:[1,1,0]
	v_mov_b32_e32 v30, v36
	v_mov_b32_e32 v34, v40
	v_mov_b32_e32 v35, v10
